# row-max permlane reduction reordered to drop two s_nop 1 (independent ops supply wait states); ret/hg items: LDS fragment reads prefetched one stage ahead
# baseline (speedup 1.0000x reference)
; #define MFMA(a, b, c) __builtin_amdgcn_mfma_f32_16x16x32_bf16(a, b, c, 0, 0, 0)
; DEV void hg_item(const Params& p, int h, int c, bf16_t* lds) {
;     ...
; #pragma unroll
;   for (int i = 0; i < 4; i++) *(u32x4*)(Kp + (lrow + i * 32) * PS + lc8) = vv[i];
;   __syncthreads();
;   f32x4 o[2][4];
; #pragma unroll
;   for (int i = 0; i < 2; i++)
; #pragma unroll
;     for (int j = 0; j < 4; j++) o[i][j] = (f32x4){0.f, 0.f, 0.f, 0.f};
; #pragma unroll
;   for (int ks = 0; ks < 4; ks++) {
;     bf16x8 a0 = ldfrag(As, PS, wm * 32 + lr, ks * 32 + lg * 8);
;     bf16x8 a1 = ldfrag(As, PS, wm * 32 + 16 + lr, ks * 32 + lg * 8);
; #pragma unroll
;     for (int j = 0; j < 4; j++) {
;       bf16x8 bb = ldfrag(Kp, PS, wn * 64 + j * 16 + lr, ks * 32 + lg * 8);
;       o[0][j] = MFMA(bb, a0, o[0][j]);
;       o[1][j] = MFMA(bb, a1, o[1][j]);
;     }
;   }
;   __syncthreads();
; #pragma unroll
;   for (int i = 0; i < 4; i++) {
;     *(u32x4*)(Qp + (lrow + i * 32) * PS + lc8) = scale8(qv[i], ca[i], cb2[i]);
;     *(u32x4*)(Kp + (lrow + i * 32) * PS + lc8) = sv[i];
;   }
.LBB0_694:
	s_or_b64 exec, exec, s[0:1]
	v_ashrrev_i32_e32 v82, 7, v143
	v_and_b32_e32 v84, 1, v123
	v_lshl_or_b32 v80, v82, 5, v142
	s_movk_i32 s0, 0x110
	v_lshlrev_b32_e32 v81, 6, v84
	s_waitcnt lgkmcnt(0)
	s_barrier
	ds_write_b128 v144, v[46:49] offset:34816
	ds_write_b128 v144, v[50:53] offset:43520
	ds_write_b128 v144, v[54:57] offset:52224
	ds_write_b128 v144, v[58:61] offset:60928
	v_mul_lo_u32 v90, v80, s0
	v_readlane_b32 s1, v255, 8
	v_or_b32_e32 v46, v81, v142
	v_mul_u32_u24_e32 v106, 0x110, v46
	v_add_u32_e32 v86, s1, v90
	v_add_u32_e32 v50, v86, v109
	v_add3_u32 v87, 0, v109, v106
	s_waitcnt lgkmcnt(0)
	s_barrier
	ds_read_b128 v[46:49], v50
	ds_read_b128 v[50:53], v50 offset:4352
	ds_read_b128 v[54:57], v87 offset:34816
	ds_read_b128 v[64:67], v87 offset:39168
	ds_read_b128 v[72:75], v87 offset:43520
	ds_read_b128 v[92:95], v87 offset:47872
	v_add_u32_e32 v88, v86, v85
	v_add3_u32 v89, 0, v85, v106
	s_waitcnt lgkmcnt(3)
	v_mfma_f32_16x16x32_bf16 v[58:61], v[54:57], v[46:49], 0
	v_lshlrev_b32_e32 v91, 1, v62
	v_and_b32_e32 v83, 63, v143
	v_cmp_gt_u32_e32 vcc, 16, v83
	v_mfma_f32_16x16x32_bf16 v[54:57], v[54:57], v[50:53], 0
	s_waitcnt lgkmcnt(2)
	v_mfma_f32_16x16x32_bf16 v[68:71], v[64:67], v[46:49], 0
	v_mfma_f32_16x16x32_bf16 v[64:67], v[64:67], v[50:53], 0
	s_waitcnt lgkmcnt(1)
	v_mfma_f32_16x16x32_bf16 v[76:79], v[72:75], v[46:49], 0
	v_mfma_f32_16x16x32_bf16 v[72:75], v[72:75], v[50:53], 0
	s_waitcnt lgkmcnt(0)
	v_mfma_f32_16x16x32_bf16 v[46:49], v[92:95], v[46:49], 0
	v_mfma_f32_16x16x32_bf16 v[50:53], v[92:95], v[50:53], 0
	ds_read_b128 v[92:95], v88
	ds_read_b128 v[96:99], v88 offset:4352
	ds_read_b128 v[224:227], v89 offset:34816
	ds_read_b128 v[220:223], v89 offset:39168
	s_waitcnt lgkmcnt(1)
	v_mfma_f32_16x16x32_bf16 v[58:61], v[224:227], v[92:95], v[58:61]
	v_mfma_f32_16x16x32_bf16 v[54:57], v[224:227], v[96:99], v[54:57]
	ds_read_b128 v[100:103], v89 offset:43520
	s_waitcnt lgkmcnt(1)
	v_mfma_f32_16x16x32_bf16 v[68:71], v[220:223], v[92:95], v[68:71]
	v_mfma_f32_16x16x32_bf16 v[64:67], v[220:223], v[96:99], v[64:67]
	s_waitcnt lgkmcnt(0)
	v_mfma_f32_16x16x32_bf16 v[76:79], v[100:103], v[92:95], v[76:79]
	v_mfma_f32_16x16x32_bf16 v[72:75], v[100:103], v[96:99], v[72:75]
	ds_read_b128 v[100:103], v89 offset:47872
	s_waitcnt lgkmcnt(0)
	v_mfma_f32_16x16x32_bf16 v[46:49], v[100:103], v[92:95], v[46:49]
	v_lshlrev_b32_e32 v92, 1, v63
	v_add_u32_e32 v63, v86, v92
	v_add3_u32 v88, 0, v92, v106
	v_mfma_f32_16x16x32_bf16 v[50:53], v[100:103], v[96:99], v[50:53]
	ds_read_b128 v[94:97], v63
	ds_read_b128 v[98:101], v63 offset:4352
	ds_read_b128 v[102:105], v88 offset:34816
	s_waitcnt lgkmcnt(0)
	v_mfma_f32_16x16x32_bf16 v[58:61], v[102:105], v[94:97], v[58:61]
	v_mfma_f32_16x16x32_bf16 v[54:57], v[102:105], v[98:101], v[54:57]
	ds_read_b128 v[102:105], v88 offset:39168
	s_waitcnt lgkmcnt(0)
	v_mfma_f32_16x16x32_bf16 v[138:141], v[102:105], v[94:97], v[68:71]
	s_nop 2
	ds_read_b128 v[68:71], v88 offset:43520
	v_mfma_f32_16x16x32_bf16 v[64:67], v[102:105], v[98:101], v[64:67]
	s_waitcnt lgkmcnt(0)
	v_mfma_f32_16x16x32_bf16 v[102:105], v[68:71], v[94:97], v[76:79]
	s_nop 2
	v_mad_u64_u32 v[78:79], s[0:1], v122, s0, v[0:1]
	v_mul_f32_e32 v0, 0x3fb8aa3b, v34
	v_exp_f32_e32 v34, v0
	v_mul_f32_e32 v0, 0x3fb8aa3b, v35
	v_exp_f32_e32 v35, v0
	v_mul_f32_e32 v0, 0x3fb8aa3b, v36
	v_exp_f32_e32 v36, v0
	v_mul_f32_e32 v0, 0x3fb8aa3b, v37
	v_exp_f32_e32 v37, v0
	v_mul_f32_e32 v0, 0x3fb8aa3b, v30
	v_exp_f32_e32 v30, v0
	v_mul_f32_e32 v0, 0x3fb8aa3b, v31
	v_exp_f32_e32 v31, v0
	v_pk_mul_f32 v[34:35], v[34:35], v[136:137]
	v_pk_mul_f32 v[36:37], v[36:37], v[132:133]
	v_mul_f32_e32 v0, 0x3fb8aa3b, v32
	v_pk_mul_f32 v[30:31], v[30:31], v[134:135]
	v_cvt_pk_bf16_f32 v34, v34, v35
	v_cvt_pk_bf16_f32 v35, v36, v37
	v_cvt_pk_bf16_f32 v36, v30, v31
	v_exp_f32_e32 v30, v0
	v_mul_f32_e32 v0, 0x3fb8aa3b, v33
	v_exp_f32_e32 v31, v0
	v_mul_f32_e32 v0, 0x3fb8aa3b, v18
	v_exp_f32_e32 v18, v0
	v_mul_f32_e32 v0, 0x3fb8aa3b, v19
	v_exp_f32_e32 v19, v0
	v_mul_f32_e32 v0, 0x3fb8aa3b, v20
	v_exp_f32_e32 v20, v0
	v_mul_f32_e32 v0, 0x3fb8aa3b, v21
	v_exp_f32_e32 v21, v0
	v_mul_f32_e32 v0, 0x3fb8aa3b, v10
	v_exp_f32_e32 v10, v0
	v_mul_f32_e32 v0, 0x3fb8aa3b, v11
	v_exp_f32_e32 v11, v0
	v_pk_mul_f32 v[18:19], v[18:19], v[130:131]
	v_pk_mul_f32 v[20:21], v[20:21], v[120:121]
	v_mul_f32_e32 v0, 0x3fb8aa3b, v12
	v_pk_mul_f32 v[10:11], v[10:11], v[126:127]
	v_mfma_f32_16x16x32_bf16 v[144:147], v[68:71], v[98:101], v[72:75]
	ds_read_b128 v[68:71], v88 offset:47872
	v_cvt_pk_bf16_f32 v18, v18, v19
	v_cvt_pk_bf16_f32 v19, v20, v21
	v_cvt_pk_bf16_f32 v20, v10, v11
	v_exp_f32_e32 v10, v0
	v_mul_f32_e32 v0, 0x3fb8aa3b, v13
	v_exp_f32_e32 v11, v0
	v_mul_f32_e32 v0, 0x3fb8aa3b, v14
	s_waitcnt lgkmcnt(0)
	v_mfma_f32_16x16x32_bf16 v[94:97], v[68:71], v[94:97], v[46:49]
	v_mul_f32_e64 v10, v10, v118
	v_mul_f32_e64 v11, v11, v119
	v_pk_mul_f32 v[30:31], v[30:31], v[128:129]
	v_cvt_pk_bf16_f32 v21, v10, v11
	v_exp_f32_e32 v10, v0
	v_mul_f32_e32 v0, 0x3fb8aa3b, v15
	v_exp_f32_e32 v11, v0
	v_mul_f32_e32 v0, 0x3fb8aa3b, v16
	v_exp_f32_e32 v12, v0
	v_mul_f32_e32 v0, 0x3fb8aa3b, v17
	v_add_u32_e32 v46, v86, v91
	v_add3_u32 v86, 0, v91, v106
	v_exp_f32_e32 v13, v0
	v_mul_f32_e32 v0, 0x3fb8aa3b, v6
	ds_read_b128 v[148:151], v46
	ds_read_b128 v[152:155], v46 offset:4352
	ds_read_b128 v[46:49], v86 offset:34816
	v_exp_f32_e32 v6, v0
	v_mul_f32_e32 v0, 0x3fb8aa3b, v7
	v_exp_f32_e32 v7, v0
	v_pk_mul_f32 v[10:11], v[10:11], v[124:125]
	v_pk_mul_f32 v[12:13], v[12:13], v[112:113]
	v_mul_f32_e32 v0, 0x3fb8aa3b, v8
	v_pk_mul_f32 v[6:7], v[6:7], v[114:115]
	v_cvt_pk_bf16_f32 v10, v10, v11
	v_cvt_pk_bf16_f32 v11, v12, v13
	v_cvt_pk_bf16_f32 v12, v6, v7
	v_exp_f32_e32 v6, v0
	v_mul_f32_e32 v0, 0x3fb8aa3b, v9
	v_exp_f32_e32 v7, v0
	v_mfma_f32_16x16x32_bf16 v[98:101], v[68:71], v[98:101], v[50:53]
	v_add_u32_e32 v0, 0, v90
	v_cvt_pk_bf16_f32 v37, v30, v31
	v_pk_mul_f32 v[6:7], v[6:7], v[110:111]
	ds_read_b128 v[50:53], v86 offset:39168
	s_waitcnt lgkmcnt(1)
	v_mfma_f32_16x16x32_bf16 v[70:73], v[46:49], v[148:151], v[58:61]
	v_cvt_pk_bf16_f32 v13, v6, v7
	v_add_u32_e32 v6, v0, v109
	v_readlane_b32 s0, v255, 9
	v_mfma_f32_16x16x32_bf16 v[74:77], v[46:49], v[152:155], v[54:57]
	ds_read_b128 v[58:61], v86 offset:47872
	s_nop 1
	ds_read_b128 v[54:57], v86 offset:43520
	s_waitcnt lgkmcnt(0)
	s_barrier
; #define MFMA(a, b, c) __builtin_amdgcn_mfma_f32_16x16x32_bf16(a, b, c, 0, 0, 0)
; DEV float shfl_xor_l(float v, int m, int lane) { return __int_as_float(__builtin_amdgcn_ds_bpermute((lane ^ m) << 2, __float_as_int(v))); }
; DEV void hg_item(const Params& p, int h, int c, bf16_t* lds) {
;     ...
; #pragma unroll
;   for (int i = 0; i < 4; i++) {
;     *(u32x4*)(Qp + (lrow + i * 32) * PS + lc8) = scale8(qv[i], ca[i], cb2[i]);
;     *(u32x4*)(Kp + (lrow + i * 32) * PS + lc8) = sv[i];
;   }
;   __syncthreads();
; #pragma unroll
;   for (int ks = 0; ks < 4; ks++) {
;     bf16x8 a0 = ldfrag(Qp, PS, wm * 32 + lr, ks * 32 + lg * 8);
;     bf16x8 a1 = ldfrag(Qp, PS, wm * 32 + 16 + lr, ks * 32 + lg * 8);
; #pragma unroll
;     for (int j = 0; j < 4; j++) {
;       bf16x8 bb = ldfrag(Kp, PS, wn * 64 + j * 16 + lr, ks * 32 + lg * 8);
;       o[0][j] = MFMA(bb, a0, o[0][j]);
;       o[1][j] = MFMA(bb, a1, o[1][j]);
;     }
;   }
; #pragma unroll
;   for (int i = 0; i < 2; i++) {
;     float ss = 0.f;
; #pragma unroll
;     for (int j = 0; j < 4; j++)
; #pragma unroll
;       for (int r = 0; r < 4; r++) ss += o[i][j][r] * o[i][j][r];
;     ss += shfl_xor_l(ss, 16, lane);
;     ss += shfl_xor_l(ss, 32, lane);
;     if (lg == 0) RED[(wm * 32 + i * 16 + lr) * 2 + wn] = ss;
;   }
	ds_write_b128 v78, v[42:45]
	ds_write_b128 v78, v[38:41] offset:34816
	ds_write_b128 v78, v[34:37] offset:8704
	ds_write_b128 v78, v[26:29] offset:43520
	ds_write_b128 v78, v[18:21] offset:17408
	ds_write_b128 v78, v[22:25] offset:52224
	ds_write_b128 v78, v[10:13] offset:26112
	ds_write_b128 v78, v[2:5] offset:60928
	s_waitcnt lgkmcnt(0)
	s_barrier
	ds_read_b128 v[2:5], v6
	ds_read_b128 v[6:9], v6 offset:4352
	ds_read_b128 v[10:13], v87 offset:34816
	ds_read_b128 v[18:21], v87 offset:39168
	ds_read_b128 v[26:29], v87 offset:43520
	ds_read_b128 v[34:37], v87 offset:47872
	v_mfma_f32_16x16x32_bf16 v[46:49], v[50:53], v[148:151], v[138:141]
	v_add_u32_e32 v38, v0, v85
	v_mfma_f32_16x16x32_bf16 v[50:53], v[50:53], v[152:155], v[64:67]
	v_mfma_f32_16x16x32_bf16 v[62:65], v[54:57], v[148:151], v[102:105]
	v_mfma_f32_16x16x32_bf16 v[66:69], v[54:57], v[152:155], v[144:147]
	v_mfma_f32_16x16x32_bf16 v[54:57], v[58:61], v[148:151], v[94:97]
	v_mfma_f32_16x16x32_bf16 v[58:61], v[58:61], v[152:155], v[98:101]
	s_waitcnt lgkmcnt(3)
	v_mfma_f32_16x16x32_bf16 v[14:17], v[10:13], v[2:5], v[70:73]
	v_mfma_f32_16x16x32_bf16 v[10:13], v[10:13], v[6:9], v[74:77]
	s_waitcnt lgkmcnt(2)
	v_mfma_f32_16x16x32_bf16 v[22:25], v[18:21], v[2:5], v[46:49]
	v_mfma_f32_16x16x32_bf16 v[18:21], v[18:21], v[6:9], v[50:53]
	s_waitcnt lgkmcnt(1)
	v_mfma_f32_16x16x32_bf16 v[30:33], v[26:29], v[2:5], v[62:65]
	v_mfma_f32_16x16x32_bf16 v[26:29], v[26:29], v[6:9], v[66:69]
	s_waitcnt lgkmcnt(0)
	v_mfma_f32_16x16x32_bf16 v[2:5], v[34:37], v[2:5], v[54:57]
	v_mfma_f32_16x16x32_bf16 v[6:9], v[34:37], v[6:9], v[58:61]
	ds_read_b128 v[34:37], v38
	ds_read_b128 v[38:41], v38 offset:4352
	ds_read_b128 v[224:227], v89 offset:34816
	ds_read_b128 v[220:223], v89 offset:39168
	s_waitcnt lgkmcnt(1)
	v_mfma_f32_16x16x32_bf16 v[14:17], v[224:227], v[34:37], v[14:17]
	v_mfma_f32_16x16x32_bf16 v[10:13], v[224:227], v[38:41], v[10:13]
	ds_read_b128 v[42:45], v89 offset:43520
	s_waitcnt lgkmcnt(1)
	v_mfma_f32_16x16x32_bf16 v[22:25], v[220:223], v[34:37], v[22:25]
	v_mfma_f32_16x16x32_bf16 v[18:21], v[220:223], v[38:41], v[18:21]
	s_waitcnt lgkmcnt(0)
	v_mfma_f32_16x16x32_bf16 v[30:33], v[42:45], v[34:37], v[30:33]
	v_mfma_f32_16x16x32_bf16 v[26:29], v[42:45], v[38:41], v[26:29]
	ds_read_b128 v[42:45], v89 offset:47872
	s_waitcnt lgkmcnt(0)
	v_mfma_f32_16x16x32_bf16 v[6:9], v[42:45], v[38:41], v[6:9]
	v_add_u32_e32 v38, v0, v92
	v_add_u32_e32 v0, v0, v91
	v_mfma_f32_16x16x32_bf16 v[2:5], v[42:45], v[34:37], v[2:5]
	ds_read_b128 v[34:37], v38
	ds_read_b128 v[38:41], v38 offset:4352
	ds_read_b128 v[42:45], v88 offset:34816
	s_waitcnt lgkmcnt(0)
	v_mfma_f32_16x16x32_bf16 v[14:17], v[42:45], v[34:37], v[14:17]
	v_mfma_f32_16x16x32_bf16 v[10:13], v[42:45], v[38:41], v[10:13]
	ds_read_b128 v[42:45], v88 offset:39168
	s_waitcnt lgkmcnt(0)
	v_mfma_f32_16x16x32_bf16 v[22:25], v[42:45], v[34:37], v[22:25]
	v_mfma_f32_16x16x32_bf16 v[42:45], v[42:45], v[38:41], v[18:21]
	s_nop 2
	ds_read_b128 v[18:21], v88 offset:43520
	s_waitcnt lgkmcnt(0)
	v_mfma_f32_16x16x32_bf16 v[30:33], v[18:21], v[34:37], v[30:33]
	v_mfma_f32_16x16x32_bf16 v[46:49], v[18:21], v[38:41], v[26:29]
	ds_read_b128 v[18:21], v88 offset:47872
	s_waitcnt lgkmcnt(0)
	v_mfma_f32_16x16x32_bf16 v[34:37], v[18:21], v[34:37], v[2:5]
	ds_read_b128 v[50:53], v0
	ds_read_b128 v[54:57], v0 offset:4352
	s_nop 0
	ds_read_b128 v[2:5], v86 offset:34816
	v_lshlrev_b32_e32 v0, 2, v83
	v_mfma_f32_16x16x32_bf16 v[38:41], v[18:21], v[38:41], v[6:9]
	s_waitcnt lgkmcnt(0)
	v_mfma_f32_16x16x32_bf16 v[18:21], v[2:5], v[50:53], v[14:17]
	s_nop 0
	ds_read_b128 v[6:9], v86 offset:39168
	v_mfma_f32_16x16x32_bf16 v[2:5], v[2:5], v[54:57], v[10:13]
	ds_read_b128 v[14:17], v86 offset:47872
	s_nop 1
	ds_read_b128 v[10:13], v86 offset:43520
	s_waitcnt lgkmcnt(2)
	v_mfma_f32_16x16x32_bf16 v[22:25], v[6:9], v[50:53], v[22:25]
	s_waitcnt lgkmcnt(0)
	v_mfma_f32_16x16x32_bf16 v[26:29], v[10:13], v[50:53], v[30:33]
	v_mfma_f32_16x16x32_bf16 v[30:33], v[14:17], v[50:53], v[34:37]
	s_nop 2
	v_mul_f32_e32 v36, v19, v19
	v_fmac_f32_e32 v36, v18, v18
	v_fmac_f32_e32 v36, v20, v20
	v_fmac_f32_e32 v36, v21, v21
	v_fmac_f32_e32 v36, v22, v22
	v_fmac_f32_e32 v36, v23, v23
	v_fmac_f32_e32 v36, v24, v24
	v_fmac_f32_e32 v36, v25, v25
	v_fmac_f32_e32 v36, v26, v26
	v_fmac_f32_e32 v36, v27, v27
	v_fmac_f32_e32 v36, v28, v28
	v_fmac_f32_e32 v36, v29, v29
	v_fmac_f32_e32 v36, v30, v30
	v_fmac_f32_e32 v36, v31, v31
	v_fmac_f32_e32 v36, v32, v32
	v_xor_b32_e32 v34, 64, v0
	v_fmac_f32_e32 v36, v33, v33
	ds_bpermute_b32 v37, v34, v36
	v_xor_b32_e32 v0, 0x80, v0
	v_mfma_f32_16x16x32_bf16 v[6:9], v[6:9], v[54:57], v[42:45]
	v_lshl_add_u32 v35, v84, 2, s0
	s_waitcnt lgkmcnt(0)
	v_add_f32_e32 v36, v36, v37
	ds_bpermute_b32 v37, v0, v36
	v_mfma_f32_16x16x32_bf16 v[10:13], v[10:13], v[54:57], v[46:49]
	v_mfma_f32_16x16x32_bf16 v[14:17], v[14:17], v[54:57], v[38:41]
	s_nop 2
	v_lshlrev_b32_e32 v38, 8, v82
	v_lshlrev_b32_e32 v39, 3, v142
	v_add3_u32 v35, v35, v38, v39
	s_and_saveexec_b64 s[0:1], vcc
	s_cbranch_execz .LBB0_696
	s_waitcnt lgkmcnt(0)
	v_add_f32_e32 v36, v36, v37
	ds_write_b32 v35, v36

; DEV float ex2(float x) { return __builtin_amdgcn_exp2f(x); }
; DEV void ret_item(const Params& p, int h, int c, bf16_t* lds) {
;     ...
;   const int lrow = tid >> 4, lc8 = (tid & 15) * 8;
;   const float l2g = log2f(1.f - ex2(-5.f - (float)h));
; #pragma unroll
;   for (int i = 0; i < 4; i++) {
;     const int row = lrow + i * 32;
;     *(uint4*)(Qs + row * PS + lc8) = *(const uint4*)(RQ + (size_t)(t0 + row) * 512 + h * 128 + lc8);
;     *(uint4*)(Ks + row * PS + lc8) = *(const uint4*)(RK + (size_t)(t0 + row) * 512 + h * 128 + lc8);
;   }
; #pragma unroll
;   for (int i = 0; i < 8; i++) {
;     const int row = lrow + i * 32;
;     *(uint4*)(Big + row * PS + lc8) = *(const uint4*)(STR + ((size_t)(h * 65 + c) * 256 + row) * 128 + lc8);
;   }
;   u32x4 vpre[8];
; #pragma unroll
;   for (int i = 0; i < 8; i++) vpre[i] = *(const u32x4*)(RVT + (size_t)(h * 256 + lrow + i * 32) * LT + t0 + lc8);
;   __syncthreads();
.LBB0_699:
	s_and_b64 vcc, exec, s[0:1]
	s_cbranch_vccz .LBB0_716
	s_add_i32 s1, s2, 0xfffffdf8
	s_and_b32 s0, s2, 3
	s_lshr_b32 s1, s1, 2
	v_mov_b32_e32 v138, v181
	s_lshl_b32 s3, s1, 7
	s_lshl_b32 s6, s0, 8
	s_add_u32 s8, s96, s6
	v_lshlrev_b32_e32 v0, 4, v138
	v_ashrrev_i32_e32 v66, 4, v138
	s_addc_u32 s9, s97, 0
	v_and_b32_e32 v0, 0xf0, v0
	v_lshl_add_u64 v[26:27], s[8:9], 0, v[0:1]
	v_readlane_b32 s8, v254, 30
	v_add_u32_e32 v34, 32, v66
	v_add_u32_e32 v42, 64, v66
	v_add_u32_e32 v44, 0x60, v66
	v_readlane_b32 s9, v254, 31
	s_add_u32 s8, s8, s6
	v_add_u32_e32 v2, s3, v66
	v_add_u32_e32 v10, s3, v34
	v_add_u32_e32 v18, s3, v42
	v_add_u32_e32 v30, s3, v44
	s_addc_u32 s9, s9, 0
	v_ashrrev_i32_e32 v3, 31, v2
	v_ashrrev_i32_e32 v11, 31, v10
	v_ashrrev_i32_e32 v19, 31, v18
	v_ashrrev_i32_e32 v31, 31, v30
	v_lshl_add_u64 v[28:29], s[8:9], 0, v[0:1]
	v_lshlrev_b64 v[2:3], 10, v[2:3]
	v_lshlrev_b64 v[10:11], 10, v[10:11]
	v_lshlrev_b64 v[18:19], 10, v[18:19]
	v_lshlrev_b64 v[30:31], 10, v[30:31]
	v_lshl_add_u64 v[4:5], v[26:27], 0, v[2:3]
	v_lshl_add_u64 v[6:7], v[28:29], 0, v[2:3]
	v_lshl_add_u64 v[12:13], v[26:27], 0, v[10:11]
	v_lshl_add_u64 v[14:15], v[28:29], 0, v[10:11]
	v_lshl_add_u64 v[20:21], v[26:27], 0, v[18:19]
	v_lshl_add_u64 v[22:23], v[28:29], 0, v[18:19]
	v_lshl_add_u64 v[26:27], v[26:27], 0, v[30:31]
	v_lshl_add_u64 v[30:31], v[28:29], 0, v[30:31]
	global_load_dwordx4 v[2:5], v[4:5], off
	s_nop 0
	global_load_dwordx4 v[6:9], v[6:7], off
	s_nop 0
	global_load_dwordx4 v[10:13], v[12:13], off
	s_nop 0
	global_load_dwordx4 v[14:17], v[14:15], off
	s_nop 0
	global_load_dwordx4 v[18:21], v[20:21], off
	s_nop 0
	global_load_dwordx4 v[22:25], v[22:23], off
	s_nop 0
	global_load_dwordx4 v[26:29], v[26:27], off
	s_nop 0
	global_load_dwordx4 v[30:33], v[30:31], off
	s_mul_i32 s7, s0, 0x41
	s_add_i32 s7, s7, s1
	v_add_u32_e32 v50, 0x80, v66
	v_add_u32_e32 v52, 0xa0, v66
	v_add_u32_e32 v60, 0xc0, v66
	v_add_u32_e32 v62, 0xe0, v66
	s_lshl_b32 s82, s7, 8
	v_readlane_b32 s8, v254, 45
	v_ashrrev_i32_e32 v67, 31, v66
	v_ashrrev_i32_e32 v35, 31, v34
	v_ashrrev_i32_e32 v43, 31, v42
	v_ashrrev_i32_e32 v45, 31, v44
	v_ashrrev_i32_e32 v51, 31, v50
	v_ashrrev_i32_e32 v53, 31, v52
	v_ashrrev_i32_e32 v61, 31, v60
	v_ashrrev_i32_e32 v63, 31, v62
	v_readlane_b32 s9, v254, 46
	v_lshl_add_u64 v[36:37], v[66:67], 0, s[82:83]
	v_lshl_add_u64 v[34:35], v[34:35], 0, s[82:83]
	v_lshl_add_u64 v[42:43], v[42:43], 0, s[82:83]
	v_lshl_add_u64 v[44:45], v[44:45], 0, s[82:83]
	v_lshl_add_u64 v[50:51], v[50:51], 0, s[82:83]
	v_lshl_add_u64 v[52:53], v[52:53], 0, s[82:83]
	v_lshl_add_u64 v[60:61], v[60:61], 0, s[82:83]
	v_lshl_add_u64 v[62:63], v[62:63], 0, s[82:83]
	v_lshl_add_u64 v[58:59], s[8:9], 0, v[0:1]
	v_lshlrev_b64 v[36:37], 8, v[36:37]
	v_lshlrev_b64 v[34:35], 8, v[34:35]
	v_lshlrev_b64 v[42:43], 8, v[42:43]
	v_lshlrev_b64 v[44:45], 8, v[44:45]
	v_lshlrev_b64 v[50:51], 8, v[50:51]
	v_lshlrev_b64 v[52:53], 8, v[52:53]
	v_lshlrev_b64 v[60:61], 8, v[60:61]
	v_lshlrev_b64 v[62:63], 8, v[62:63]
	v_lshl_add_u64 v[36:37], v[58:59], 0, v[36:37]
	v_lshl_add_u64 v[38:39], v[58:59], 0, v[34:35]
	v_lshl_add_u64 v[42:43], v[58:59], 0, v[42:43]
	v_lshl_add_u64 v[46:47], v[58:59], 0, v[44:45]
	v_lshl_add_u64 v[50:51], v[58:59], 0, v[50:51]
	v_lshl_add_u64 v[54:55], v[58:59], 0, v[52:53]
	v_lshl_add_u64 v[60:61], v[58:59], 0, v[60:61]
	v_lshl_add_u64 v[62:63], v[58:59], 0, v[62:63]
	global_load_dwordx4 v[34:37], v[36:37], off
	s_nop 0
	global_load_dwordx4 v[38:41], v[38:39], off
	s_nop 0
	global_load_dwordx4 v[42:45], v[42:43], off
	s_nop 0
	global_load_dwordx4 v[46:49], v[46:47], off
	s_nop 0
	global_load_dwordx4 v[50:53], v[50:51], off
	s_nop 0
	global_load_dwordx4 v[54:57], v[54:55], off
	s_nop 0
	global_load_dwordx4 v[58:61], v[60:61], off
	s_nop 0
	global_load_dwordx4 v[62:65], v[62:63], off
	s_movk_i32 s10, 0x110
	v_mul_lo_u32 v67, v66, s10
	s_lshl_b32 s1, s1, 8
	v_readlane_b32 s7, v254, 43
	v_add3_u32 v68, 0, v0, v67
	s_add_u32 s8, s7, s1
	v_readlane_b32 s1, v254, 44
	s_waitcnt vmcnt(15)
	ds_write_b128 v68, v[2:5]
	s_waitcnt vmcnt(14)
	ds_write_b128 v68, v[6:9] offset:34816
	s_waitcnt vmcnt(13)
	ds_write_b128 v68, v[10:13] offset:8704
	s_waitcnt vmcnt(12)
	ds_write_b128 v68, v[14:17] offset:43520
	s_waitcnt vmcnt(11)
	ds_write_b128 v68, v[18:21] offset:17408
	s_waitcnt vmcnt(10)
	ds_write_b128 v68, v[22:25] offset:52224
	s_waitcnt vmcnt(9)
	ds_write_b128 v68, v[26:29] offset:26112
	s_waitcnt vmcnt(8)
	ds_write_b128 v68, v[30:33] offset:60928
	v_readlane_b32 s11, v255, 8
	v_add_u32_e32 v30, s6, v66
	s_addc_u32 s9, s1, 0
	v_add3_u32 v143, s11, v0, v67
	v_lshl_add_u64 v[26:27], s[8:9], 0, v[0:1]
	v_add_u32_e32 v0, 32, v30
	v_mad_i64_i32 v[6:7], s[8:9], v0, s95, v[26:27]
	v_add_u32_e32 v0, 64, v30
	v_mad_i64_i32 v[10:11], s[8:9], v0, s95, v[26:27]
	v_add_u32_e32 v0, 0x60, v30
	v_mad_i64_i32 v[14:15], s[8:9], v0, s95, v[26:27]
	v_add_u32_e32 v0, 0x80, v30
	v_mad_i64_i32 v[18:19], s[8:9], v0, s95, v[26:27]
	v_add_u32_e32 v0, 0xa0, v30
	v_mad_i64_i32 v[22:23], s[8:9], v0, s95, v[26:27]
	v_add_u32_e32 v0, 0xc0, v30
	v_mad_i64_i32 v[28:29], s[8:9], v0, s95, v[26:27]
	v_add_u32_e32 v0, 0xe0, v30
	s_waitcnt vmcnt(7)
	ds_write_b128 v143, v[34:37]
	s_waitcnt vmcnt(6)
	ds_write_b128 v143, v[38:41] offset:8704
	s_waitcnt vmcnt(5)
	ds_write_b128 v143, v[42:45] offset:17408
	s_waitcnt vmcnt(4)
	ds_write_b128 v143, v[46:49] offset:26112
	s_waitcnt vmcnt(3)
	ds_write_b128 v143, v[50:53] offset:34816
	s_waitcnt vmcnt(2)
	ds_write_b128 v143, v[54:57] offset:43520
	s_waitcnt vmcnt(1)
	ds_write_b128 v143, v[58:61] offset:52224
	s_waitcnt vmcnt(0)
	ds_write_b128 v143, v[62:65] offset:60928
	v_mad_i64_i32 v[2:3], s[8:9], v30, s95, v[26:27]
	v_mad_i64_i32 v[30:31], s[8:9], v0, s95, v[26:27]
	global_load_dwordx4 v[2:5], v[2:3], off
	s_nop 0
	global_load_dwordx4 v[6:9], v[6:7], off
	s_nop 0
	global_load_dwordx4 v[10:13], v[10:11], off
	s_nop 0
	global_load_dwordx4 v[14:17], v[14:15], off
	s_nop 0
	global_load_dwordx4 v[18:21], v[18:19], off
	s_nop 0
	global_load_dwordx4 v[22:25], v[22:23], off
	s_nop 0
	global_load_dwordx4 v[26:29], v[28:29], off
	s_nop 0
	global_load_dwordx4 v[30:33], v[30:31], off
	v_bfe_u32 v134, v138, 6, 1
	v_and_b32_e32 v132, 15, v138
	v_lshlrev_b32_e32 v0, 6, v134
	v_and_b32_e32 v144, 48, v138
	v_or_b32_e32 v34, v0, v132
	v_add_u32_e32 v38, 0, v144
	v_mad_u32_u24 v146, v34, s10, v38
	v_ashrrev_i32_e32 v131, 7, v138
	s_waitcnt lgkmcnt(0)
	s_barrier
; #define MFMA(a, b, c) __builtin_amdgcn_mfma_f32_16x16x32_bf16(a, b, c, 0, 0, 0)
; DEV void ret_item(const Params& p, int h, int c, bf16_t* lds) {
;     ...
; #pragma unroll
;   for (int ks = 0; ks < 4; ks++) {
;     bf16x8 a0 = ldfrag(Qs, PS, wm * 32 + lr, ks * 32 + lg * 8);
;     bf16x8 a1 = ldfrag(Qs, PS, wm * 32 + 16 + lr, ks * 32 + lg * 8);
; #pragma unroll
;     for (int j = 0; j < 4; j++) {
;       bf16x8 bb = ldfrag(Ks, PS, wn * 64 + j * 16 + lr, ks * 32 + lg * 8);
;       s[0][j] = MFMA(bb, a0, s[0][j]);
;       s[1][j] = MFMA(bb, a1, s[1][j]);
;     }
; #pragma unroll
;     for (int j = 0; j < 8; j++) {
;       bf16x8 bb = ldfrag(Big, PS, wn * 128 + j * 16 + lr, ks * 32 + lg * 8);
;       o[0][j] = MFMA(bb, a0, o[0][j]);
;       o[1][j] = MFMA(bb, a1, o[1][j]);
;     }
;     __builtin_amdgcn_sched_barrier(0);
;   }
	ds_read_b128 v[34:37], v146 offset:34816
	v_lshlrev_b32_e32 v133, 7, v134
	v_lshl_or_b32 v130, v131, 5, v132
	v_or_b32_e32 v139, v133, v132
	v_mov_b32_e32 v74, s11
	v_mul_lo_u32 v147, v130, s10
	v_mad_u32_u24 v149, v139, s10, v74
	v_add_u32_e32 v136, v38, v147
	v_add_u32_e32 v137, v149, v144
	ds_read_b128 v[38:41], v136
	ds_read_b128 v[42:45], v136 offset:4352
	ds_read_b128 v[46:49], v146 offset:39168
	ds_read_b128 v[58:61], v146 offset:43520
	ds_read_b128 v[62:65], v146 offset:47872
	ds_read_b128 v[74:77], v137
	ds_read_b128 v[78:81], v137 offset:4352
	ds_read_b128 v[90:93], v137 offset:8704
	ds_read_b128 v[94:97], v137 offset:13056
	ds_read_b128 v[106:109], v137 offset:17408
	ds_read_b128 v[110:113], v137 offset:21760
	ds_read_b128 v[122:125], v137 offset:26112
	ds_read_b128 v[126:129], v137 offset:30464
	v_cvt_f32_ubyte0_e32 v135, s0
	v_sub_f32_e32 v135, 0xc0a00000, v135
	s_waitcnt lgkmcnt(12)
	v_mfma_f32_16x16x32_bf16 v[50:53], v[34:37], v[38:41], 0
	v_exp_f32_e32 v140, v135
	v_bfe_u32 v145, v138, 4, 2
	v_and_b32_e32 v135, 63, v138
	s_waitcnt lgkmcnt(11)
	v_mfma_f32_16x16x32_bf16 v[34:37], v[34:37], v[42:45], 0
	v_sub_f32_e32 v178, 1.0, v140
	v_lshlrev_b32_e32 v148, 3, v145
	v_mul_u32_u24_e32 v179, 0x110, v139
	s_waitcnt lgkmcnt(10)
	v_mfma_f32_16x16x32_bf16 v[54:57], v[46:49], v[38:41], 0
	v_mfma_f32_16x16x32_bf16 v[46:49], v[46:49], v[42:45], 0
	s_waitcnt lgkmcnt(9)
	v_mfma_f32_16x16x32_bf16 v[66:69], v[58:61], v[38:41], 0
	v_mfma_f32_16x16x32_bf16 v[58:61], v[58:61], v[42:45], 0
	s_waitcnt lgkmcnt(8)
	v_mfma_f32_16x16x32_bf16 v[70:73], v[62:65], v[38:41], 0
	v_mfma_f32_16x16x32_bf16 v[62:65], v[62:65], v[42:45], 0
	s_waitcnt lgkmcnt(7)
	v_mfma_f32_16x16x32_bf16 v[82:85], v[74:77], v[38:41], 0
	v_mfma_f32_16x16x32_bf16 v[74:77], v[74:77], v[42:45], 0
	s_waitcnt lgkmcnt(6)
	v_mfma_f32_16x16x32_bf16 v[86:89], v[78:81], v[38:41], 0
	v_mfma_f32_16x16x32_bf16 v[78:81], v[78:81], v[42:45], 0
	s_waitcnt lgkmcnt(5)
	v_mfma_f32_16x16x32_bf16 v[98:101], v[90:93], v[38:41], 0
	v_mfma_f32_16x16x32_bf16 v[90:93], v[90:93], v[42:45], 0
	s_waitcnt lgkmcnt(4)
	v_mfma_f32_16x16x32_bf16 v[102:105], v[94:97], v[38:41], 0
	v_mfma_f32_16x16x32_bf16 v[94:97], v[94:97], v[42:45], 0
	s_waitcnt lgkmcnt(3)
	v_mfma_f32_16x16x32_bf16 v[114:117], v[106:109], v[38:41], 0
	v_mfma_f32_16x16x32_bf16 v[106:109], v[106:109], v[42:45], 0
	s_waitcnt lgkmcnt(2)
	v_mfma_f32_16x16x32_bf16 v[118:121], v[110:113], v[38:41], 0
	v_mfma_f32_16x16x32_bf16 v[110:113], v[110:113], v[42:45], 0
	s_waitcnt lgkmcnt(1)
	v_mfma_f32_16x16x32_bf16 v[150:153], v[122:125], v[38:41], 0
	v_mfma_f32_16x16x32_bf16 v[122:125], v[122:125], v[42:45], 0
	s_waitcnt lgkmcnt(0)
	v_mfma_f32_16x16x32_bf16 v[38:41], v[126:129], v[38:41], 0
	v_mfma_f32_16x16x32_bf16 v[42:45], v[126:129], v[42:45], 0
	ds_read_b128 v[126:129], v136 offset:64
	ds_read_b128 v[154:157], v136 offset:4416
	ds_read_b128 v[224:227], v146 offset:34880
	ds_read_b128 v[220:223], v146 offset:39232
	s_waitcnt lgkmcnt(1)
	v_mfma_f32_16x16x32_bf16 v[50:53], v[224:227], v[126:129], v[50:53]
	v_mfma_f32_16x16x32_bf16 v[34:37], v[224:227], v[154:157], v[34:37]
	ds_read_b128 v[224:227], v146 offset:43584
	s_waitcnt lgkmcnt(1)
	v_mfma_f32_16x16x32_bf16 v[54:57], v[220:223], v[126:129], v[54:57]
	v_mfma_f32_16x16x32_bf16 v[46:49], v[220:223], v[154:157], v[46:49]
	ds_read_b128 v[138:141], v146 offset:47936
	s_waitcnt lgkmcnt(1)
	v_mfma_f32_16x16x32_bf16 v[66:69], v[224:227], v[126:129], v[66:69]
	v_mfma_f32_16x16x32_bf16 v[58:61], v[224:227], v[154:157], v[58:61]
	s_waitcnt lgkmcnt(0)
	v_mfma_f32_16x16x32_bf16 v[70:73], v[138:141], v[126:129], v[70:73]
	v_mfma_f32_16x16x32_bf16 v[62:65], v[138:141], v[154:157], v[62:65]
	v_or_b32_e32 v138, 64, v144
	v_add_u32_e32 v140, v149, v138
	ds_read_b128 v[158:161], v140
	v_add3_u32 v138, s11, v138, v179
	s_waitcnt lgkmcnt(0)
	v_mfma_f32_16x16x32_bf16 v[82:85], v[158:161], v[126:129], v[82:85]
	v_mfma_f32_16x16x32_bf16 v[74:77], v[158:161], v[154:157], v[74:77]
	ds_read_b128 v[224:227], v138 offset:4352
	ds_read_b128 v[220:223], v138 offset:8704
	s_waitcnt lgkmcnt(1)
	v_mfma_f32_16x16x32_bf16 v[86:89], v[224:227], v[126:129], v[86:89]
	v_mfma_f32_16x16x32_bf16 v[78:81], v[224:227], v[154:157], v[78:81]
	ds_read_b128 v[224:227], v138 offset:13056
	s_waitcnt lgkmcnt(1)
	v_mfma_f32_16x16x32_bf16 v[98:101], v[220:223], v[126:129], v[98:101]
	v_mfma_f32_16x16x32_bf16 v[90:93], v[220:223], v[154:157], v[90:93]
	ds_read_b128 v[220:223], v138 offset:17408
	s_waitcnt lgkmcnt(1)
	v_mfma_f32_16x16x32_bf16 v[102:105], v[224:227], v[126:129], v[102:105]
	v_mfma_f32_16x16x32_bf16 v[94:97], v[224:227], v[154:157], v[94:97]
	ds_read_b128 v[224:227], v138 offset:21760
	s_waitcnt lgkmcnt(1)
	v_mfma_f32_16x16x32_bf16 v[114:117], v[220:223], v[126:129], v[114:117]
	v_mfma_f32_16x16x32_bf16 v[106:109], v[220:223], v[154:157], v[106:109]
	ds_read_b128 v[220:223], v138 offset:26112
	s_waitcnt lgkmcnt(1)
	v_mfma_f32_16x16x32_bf16 v[118:121], v[224:227], v[126:129], v[118:121]
	v_mfma_f32_16x16x32_bf16 v[110:113], v[224:227], v[154:157], v[110:113]
	ds_read_b128 v[158:161], v138 offset:30464
	s_waitcnt lgkmcnt(1)
	v_mfma_f32_16x16x32_bf16 v[150:153], v[220:223], v[126:129], v[150:153]
	v_mfma_f32_16x16x32_bf16 v[122:125], v[220:223], v[154:157], v[122:125]
	s_waitcnt lgkmcnt(0)
	v_mfma_f32_16x16x32_bf16 v[38:41], v[158:161], v[126:129], v[38:41]
	v_mfma_f32_16x16x32_bf16 v[42:45], v[158:161], v[154:157], v[42:45]
	ds_read_b128 v[126:129], v136 offset:128
	ds_read_b128 v[154:157], v136 offset:4480
	ds_read_b128 v[158:161], v146 offset:34944
	v_or_b32_e32 v139, 0x80, v144
	v_add_u32_e32 v142, v149, v139
	v_add3_u32 v139, s11, v139, v179
	s_waitcnt lgkmcnt(0)
; #define MFMA(a, b, c) __builtin_amdgcn_mfma_f32_16x16x32_bf16(a, b, c, 0, 0, 0)
; DEV float ex2(float x) { return __builtin_amdgcn_exp2f(x); }
; DEV void ret_item(const Params& p, int h, int c, bf16_t* lds) {
;     ...
; #pragma unroll
;   for (int ks = 0; ks < 4; ks++) {
;     bf16x8 a0 = ldfrag(Qs, PS, wm * 32 + lr, ks * 32 + lg * 8);
;     bf16x8 a1 = ldfrag(Qs, PS, wm * 32 + 16 + lr, ks * 32 + lg * 8);
; #pragma unroll
;     for (int j = 0; j < 4; j++) {
;       bf16x8 bb = ldfrag(Ks, PS, wn * 64 + j * 16 + lr, ks * 32 + lg * 8);
;       s[0][j] = MFMA(bb, a0, s[0][j]);
;       s[1][j] = MFMA(bb, a1, s[1][j]);
;     }
; #pragma unroll
;     for (int j = 0; j < 8; j++) {
;       bf16x8 bb = ldfrag(Big, PS, wn * 128 + j * 16 + lr, ks * 32 + lg * 8);
;       o[0][j] = MFMA(bb, a0, o[0][j]);
;       o[1][j] = MFMA(bb, a1, o[1][j]);
;     }
;     __builtin_amdgcn_sched_barrier(0);
;   }
; #pragma unroll
;   for (int i = 0; i < 2; i++) {
;     const int q = wm * 32 + i * 16 + lr;
;     const float qd = ex2(l2g * (float)(q + 1));
; #pragma unroll
;     for (int j = 0; j < 8; j++)
; #pragma unroll
;       for (int r = 0; r < 4; r++) o[i][j][r] *= qd;
;   }
	v_mfma_f32_16x16x32_bf16 v[50:53], v[158:161], v[126:129], v[50:53]
	v_mfma_f32_16x16x32_bf16 v[34:37], v[158:161], v[154:157], v[34:37]
	ds_read_b128 v[224:227], v146 offset:39296
	ds_read_b128 v[220:223], v146 offset:43648
	s_waitcnt lgkmcnt(1)
	v_mfma_f32_16x16x32_bf16 v[54:57], v[224:227], v[126:129], v[54:57]
	v_mfma_f32_16x16x32_bf16 v[46:49], v[224:227], v[154:157], v[46:49]
	ds_read_b128 v[158:161], v146 offset:48000
	s_waitcnt lgkmcnt(1)
	v_mfma_f32_16x16x32_bf16 v[66:69], v[220:223], v[126:129], v[66:69]
	v_mfma_f32_16x16x32_bf16 v[58:61], v[220:223], v[154:157], v[58:61]
	s_waitcnt lgkmcnt(0)
	v_mfma_f32_16x16x32_bf16 v[70:73], v[158:161], v[126:129], v[70:73]
	v_mfma_f32_16x16x32_bf16 v[62:65], v[158:161], v[154:157], v[62:65]
	ds_read_b128 v[158:161], v142
	s_waitcnt lgkmcnt(0)
	v_mfma_f32_16x16x32_bf16 v[82:85], v[158:161], v[126:129], v[82:85]
	v_mfma_f32_16x16x32_bf16 v[158:161], v[158:161], v[154:157], v[74:77]
	s_nop 2
	ds_read_b128 v[224:227], v139 offset:4352
	ds_read_b128 v[220:223], v139 offset:8704
	s_waitcnt lgkmcnt(1)
	v_mfma_f32_16x16x32_bf16 v[86:89], v[224:227], v[126:129], v[86:89]
	v_mfma_f32_16x16x32_bf16 v[78:81], v[224:227], v[154:157], v[78:81]
	ds_read_b128 v[224:227], v139 offset:13056
	s_waitcnt lgkmcnt(1)
	v_mfma_f32_16x16x32_bf16 v[98:101], v[220:223], v[126:129], v[98:101]
	v_mfma_f32_16x16x32_bf16 v[90:93], v[220:223], v[154:157], v[90:93]
	ds_read_b128 v[220:223], v139 offset:17408
	s_waitcnt lgkmcnt(1)
	v_mfma_f32_16x16x32_bf16 v[162:165], v[224:227], v[126:129], v[102:105]
	v_mfma_f32_16x16x32_bf16 v[94:97], v[224:227], v[154:157], v[94:97]
	ds_read_b128 v[224:227], v139 offset:21760
	s_waitcnt lgkmcnt(1)
	v_mfma_f32_16x16x32_bf16 v[166:169], v[220:223], v[126:129], v[114:117]
	v_mfma_f32_16x16x32_bf16 v[170:173], v[220:223], v[154:157], v[106:109]
	ds_read_b128 v[220:223], v139 offset:26112
	s_waitcnt lgkmcnt(1)
	v_mfma_f32_16x16x32_bf16 v[174:177], v[224:227], v[126:129], v[118:121]
	v_mfma_f32_16x16x32_bf16 v[182:185], v[224:227], v[154:157], v[110:113]
	ds_read_b128 v[74:77], v139 offset:30464
	s_waitcnt lgkmcnt(1)
	v_mfma_f32_16x16x32_bf16 v[150:153], v[220:223], v[126:129], v[150:153]
	v_mfma_f32_16x16x32_bf16 v[186:189], v[220:223], v[154:157], v[122:125]
	s_waitcnt lgkmcnt(0)
	v_mfma_f32_16x16x32_bf16 v[38:41], v[74:77], v[126:129], v[38:41]
	v_mfma_f32_16x16x32_bf16 v[42:45], v[74:77], v[154:157], v[42:45]
	ds_read_b128 v[154:157], v136 offset:192
	ds_read_b128 v[190:193], v136 offset:4544
	ds_read_b128 v[74:77], v146 offset:35008
	s_waitcnt lgkmcnt(0)
	v_mfma_f32_16x16x32_bf16 v[110:113], v[74:77], v[190:193], v[34:37]
	s_nop 2
	ds_read_b128 v[34:37], v146 offset:39360
	v_mfma_f32_16x16x32_bf16 v[126:129], v[74:77], v[154:157], v[50:53]
	s_waitcnt lgkmcnt(0)
	v_mfma_f32_16x16x32_bf16 v[122:125], v[34:37], v[154:157], v[54:57]
	s_nop 2
	v_or_b32_e32 v54, 0xc0, v144
	v_add_u32_e32 v144, v149, v54
	v_mfma_f32_16x16x32_bf16 v[106:109], v[34:37], v[190:193], v[46:49]
	ds_read_b128 v[34:37], v146 offset:43712
	v_add3_u32 v141, s11, v54, v179
	s_waitcnt lgkmcnt(0)
	v_mfma_f32_16x16x32_bf16 v[118:121], v[34:37], v[154:157], v[66:69]
	v_mfma_f32_16x16x32_bf16 v[102:105], v[34:37], v[190:193], v[58:61]
	ds_read_b128 v[224:227], v146 offset:48064
	ds_read_b128 v[220:223], v144
	s_waitcnt lgkmcnt(1)
	v_mfma_f32_16x16x32_bf16 v[114:117], v[224:227], v[154:157], v[70:73]
	v_mfma_f32_16x16x32_bf16 v[74:77], v[224:227], v[190:193], v[62:65]
	ds_read_b128 v[224:227], v141 offset:4352
	s_waitcnt lgkmcnt(1)
	v_mfma_f32_16x16x32_bf16 v[46:49], v[220:223], v[154:157], v[82:85]
	v_mfma_f32_16x16x32_bf16 v[50:53], v[220:223], v[190:193], v[158:161]
	ds_read_b128 v[220:223], v141 offset:8704
	s_waitcnt lgkmcnt(1)
	v_mfma_f32_16x16x32_bf16 v[54:57], v[224:227], v[154:157], v[86:89]
	v_mfma_f32_16x16x32_bf16 v[66:69], v[224:227], v[190:193], v[78:81]
	ds_read_b128 v[224:227], v141 offset:13056
	s_waitcnt lgkmcnt(1)
	v_mfma_f32_16x16x32_bf16 v[58:61], v[220:223], v[154:157], v[98:101]
	v_mfma_f32_16x16x32_bf16 v[70:73], v[220:223], v[190:193], v[90:93]
	ds_read_b128 v[220:223], v141 offset:17408
	s_waitcnt lgkmcnt(1)
	v_mfma_f32_16x16x32_bf16 v[62:65], v[224:227], v[154:157], v[162:165]
	v_mfma_f32_16x16x32_bf16 v[158:161], v[224:227], v[190:193], v[94:97]
	ds_read_b128 v[224:227], v141 offset:21760
	s_waitcnt lgkmcnt(1)
	v_mfma_f32_16x16x32_bf16 v[86:89], v[220:223], v[154:157], v[166:169]
	v_mfma_f32_16x16x32_bf16 v[162:165], v[220:223], v[190:193], v[170:173]
	ds_read_b128 v[220:223], v141 offset:26112
	s_waitcnt lgkmcnt(1)
	v_mfma_f32_16x16x32_bf16 v[90:93], v[224:227], v[154:157], v[174:177]
	v_mfma_f32_16x16x32_bf16 v[166:169], v[224:227], v[190:193], v[182:185]
	ds_read_b128 v[34:37], v141 offset:30464
	s_waitcnt lgkmcnt(1)
	v_mfma_f32_16x16x32_bf16 v[98:101], v[220:223], v[154:157], v[150:153]
	v_mfma_f32_16x16x32_bf16 v[150:153], v[220:223], v[190:193], v[186:189]
	s_waitcnt lgkmcnt(0)
	v_mfma_f32_16x16x32_bf16 v[38:41], v[34:37], v[154:157], v[38:41]
	v_mfma_f32_16x16x32_bf16 v[154:157], v[34:37], v[190:193], v[42:45]
	v_cmp_gt_f32_e32 vcc, s30, v178
	s_and_b64 s[0:1], vcc, exec
	s_cselect_b32 s0, 32, 0
	v_ldexp_f32 v34, v178, s0
	v_log_f32_e32 v34, v34
	v_cndmask_b32_e32 v35, 0, v212, vcc
	v_lshlrev_b32_e32 v145, 2, v145
	v_or_b32_e32 v149, v0, v145
	v_sub_f32_e32 v146, v34, v35
	v_add_u32_e32 v34, 1, v130
	v_cvt_f32_i32_e32 v34, v34
	v_add3_u32 v0, 0, v133, v148
	v_cmp_lt_i32_e32 vcc, v130, v149
	v_cmp_gt_i32_e64 s[0:1], v130, v149
	v_mul_f32_e32 v34, v146, v34
	v_exp_f32_e32 v36, v34
	s_mov_b32 s7, 0x5040100
	s_barrier
; DEV uint2 pack4(f32x4 v) { uint2 r; r.x = pack2(v[0], v[1]); r.y = pack2(v[2], v[3]); return r; }
; DEV float ex2(float x) { return __builtin_amdgcn_exp2f(x); }
; DEV void ret_item(const Params& p, int h, int c, bf16_t* lds) {
;     ...
; #pragma unroll
;   for (int i = 0; i < 2; i++) {
;     const int q = wm * 32 + i * 16 + lr;
;     const float qd = ex2(l2g * (float)(q + 1));
; #pragma unroll
;     for (int j = 0; j < 8; j++)
; #pragma unroll
;       for (int r = 0; r < 4; r++) o[i][j][r] *= qd;
;   }
;   __syncthreads();
; #pragma unroll
;   for (int i = 0; i < 2; i++) {
;     const int q = wm * 32 + i * 16 + lr;
; #pragma unroll
;     for (int j = 0; j < 4; j++) {
;       f32x4 v;
; #pragma unroll
;       for (int r = 0; r < 4; r++) {
;         const int key = wn * 64 + j * 16 + lg * 4 + r;
;         v[r] = (key <= q) ? s[i][j][r] * ex2(l2g * (float)(q - key)) : 0.f;
;       }
;       *(uint2*)(Ks + q * PS + wn * 64 + j * 16 + lg * 4) = pack4(v);
;     }
;   }
	v_pk_mul_f32 v[34:35], v[36:37], v[38:39] op_sel_hi:[0,1]
	v_add_u32_e32 v38, 17, v130
	v_cvt_f32_i32_e32 v38, v38
	v_pk_mul_f32 v[94:95], v[36:37], v[46:47] op_sel_hi:[0,1]
	v_pk_mul_f32 v[96:97], v[36:37], v[48:49] op_sel_hi:[0,1]
	v_pk_mul_f32 v[82:83], v[36:37], v[54:55] op_sel_hi:[0,1]
	v_mul_f32_e32 v38, v146, v38
	v_pk_mul_f32 v[84:85], v[36:37], v[56:57] op_sel_hi:[0,1]
	v_pk_mul_f32 v[78:79], v[36:37], v[58:59] op_sel_hi:[0,1]
	v_pk_mul_f32 v[80:81], v[36:37], v[60:61] op_sel_hi:[0,1]
	v_pk_mul_f32 v[62:63], v[36:37], v[62:63] op_sel_hi:[0,1]
	v_pk_mul_f32 v[64:65], v[36:37], v[64:65] op_sel_hi:[0,1]
	v_pk_mul_f32 v[58:59], v[36:37], v[86:87] op_sel_hi:[0,1]
	v_pk_mul_f32 v[60:61], v[36:37], v[88:89] op_sel_hi:[0,1]
	v_pk_mul_f32 v[46:47], v[36:37], v[90:91] op_sel_hi:[0,1]
	v_pk_mul_f32 v[48:49], v[36:37], v[92:93] op_sel_hi:[0,1]
	v_pk_mul_f32 v[42:43], v[36:37], v[98:99] op_sel_hi:[0,1]
	v_pk_mul_f32 v[44:45], v[36:37], v[100:101] op_sel_hi:[0,1]
	v_pk_mul_f32 v[36:37], v[36:37], v[40:41] op_sel_hi:[0,1]
	v_exp_f32_e32 v40, v38
	s_nop 0
	v_pk_mul_f32 v[98:99], v[40:41], v[50:51] op_sel_hi:[0,1]
	v_pk_mul_f32 v[50:51], v[40:41], v[150:151] op_sel_hi:[0,1]
	v_add_u32_e32 v151, v0, v147
	v_sub_u32_e32 v147, v130, v149
	v_cvt_f32_i32_e32 v147, v147
	v_or_b32_e32 v150, 1, v149
	v_pk_mul_f32 v[38:39], v[40:41], v[154:155] op_sel_hi:[0,1]
	v_pk_mul_f32 v[100:101], v[40:41], v[52:53] op_sel_hi:[0,1]
	v_mul_f32_e32 v147, v146, v147
	v_exp_f32_e32 v147, v147
	v_pk_mul_f32 v[52:53], v[40:41], v[152:153] op_sel_hi:[0,1]
	v_pk_mul_f32 v[90:91], v[40:41], v[66:67] op_sel_hi:[0,1]
	v_pk_mul_f32 v[92:93], v[40:41], v[68:69] op_sel_hi:[0,1]
	v_mul_f32_e32 v126, v147, v126
	v_cndmask_b32_e64 v148, v126, 0, vcc
	v_sub_u32_e32 v126, v130, v150
	v_cvt_f32_i32_e32 v126, v126
	v_pk_mul_f32 v[86:87], v[40:41], v[70:71] op_sel_hi:[0,1]
	v_pk_mul_f32 v[88:89], v[40:41], v[72:73] op_sel_hi:[0,1]
	v_pk_mul_f32 v[70:71], v[40:41], v[158:159] op_sel_hi:[0,1]
	v_mul_f32_e32 v126, v146, v126
	v_exp_f32_e32 v126, v126
	v_pk_mul_f32 v[72:73], v[40:41], v[160:161] op_sel_hi:[0,1]
	v_pk_mul_f32 v[66:67], v[40:41], v[162:163] op_sel_hi:[0,1]
	v_pk_mul_f32 v[68:69], v[40:41], v[164:165] op_sel_hi:[0,1]
	v_mul_f32_e32 v126, v126, v127
	v_cndmask_b32_e64 v154, 0, v126, s[0:1]
	v_or_b32_e32 v126, 3, v149
	v_or_b32_e32 v127, 2, v149
	v_sub_u32_e32 v152, v130, v127
	v_sub_u32_e32 v153, v130, v126
	v_cvt_f32_i32_e32 v152, v152
	v_cvt_f32_i32_e32 v153, v153
	v_cmp_ge_i32_e64 s[0:1], v130, v127
	v_pk_mul_f32 v[54:55], v[40:41], v[166:167] op_sel_hi:[0,1]
	v_mul_f32_e32 v152, v146, v152
	v_mul_f32_e32 v153, v146, v153
	v_exp_f32_e32 v152, v152
	v_exp_f32_e32 v153, v153
	v_pk_mul_f32 v[56:57], v[40:41], v[168:169] op_sel_hi:[0,1]
	v_pk_mul_f32 v[40:41], v[40:41], v[156:157] op_sel_hi:[0,1]
	v_or_b32_e32 v156, 16, v149
	v_pk_mul_f32 v[128:129], v[152:153], v[128:129]
	v_cvt_pk_bf16_f32 v152, v148, v154
	v_cvt_pk_bf16_f32 v128, v128, v129
	v_cndmask_b32_e64 v129, 0, v128, s[0:1]
	v_lshrrev_b32_e32 v128, 16, v128
	v_cmp_ge_i32_e64 s[0:1], v130, v126
	v_or_b32_e32 v148, 17, v149
	v_add_u32_e32 v151, 0x8800, v151
	v_cndmask_b32_e64 v128, 0, v128, s[0:1]
	v_perm_b32 v153, v128, v129, s7
	v_sub_u32_e32 v128, v130, v156
	v_sub_u32_e32 v129, v130, v148
	v_cvt_f32_i32_e32 v128, v128
	v_cvt_f32_i32_e32 v129, v129
	v_cmp_ge_i32_e64 s[0:1], v130, v156
	v_mul_f32_e32 v128, v146, v128
	v_mul_f32_e32 v129, v146, v129
	v_exp_f32_e32 v128, v128
	v_exp_f32_e32 v129, v129
	s_nop 0
	v_pk_mul_f32 v[122:123], v[128:129], v[122:123]
	v_or_b32_e32 v128, 19, v149
	v_or_b32_e32 v129, 18, v149
	v_sub_u32_e32 v154, v130, v129
	v_sub_u32_e32 v155, v130, v128
	v_cvt_f32_i32_e32 v154, v154
	v_cvt_f32_i32_e32 v155, v155
	v_cvt_pk_bf16_f32 v122, v122, v123
	v_mul_f32_e32 v154, v146, v154
	v_mul_f32_e32 v155, v146, v155
	v_exp_f32_e32 v154, v154
	v_exp_f32_e32 v155, v155
	s_nop 0
	v_pk_mul_f32 v[124:125], v[154:155], v[124:125]
	v_cndmask_b32_e64 v154, 0, v122, s[0:1]
	v_lshrrev_b32_e32 v122, 16, v122
	v_cmp_ge_i32_e64 s[0:1], v130, v148
	v_cvt_pk_bf16_f32 v123, v124, v125
	s_nop 0
	v_cndmask_b32_e64 v122, 0, v122, s[0:1]
	v_cmp_ge_i32_e64 s[0:1], v130, v129
	v_perm_b32 v122, v122, v154, s7
	s_nop 0
	v_cndmask_b32_e64 v124, 0, v123, s[0:1]
	v_lshrrev_b32_e32 v123, 16, v123
	v_cmp_ge_i32_e64 s[0:1], v130, v128
	s_nop 1
	v_cndmask_b32_e64 v123, 0, v123, s[0:1]
	v_perm_b32 v123, v123, v124, s7
	ds_write2_b64 v151, v[152:153], v[122:123] offset1:4
	v_or_b32_e32 v122, 33, v149
	v_or_b32_e32 v123, 32, v149
	v_sub_u32_e32 v124, v130, v123
	v_sub_u32_e32 v125, v130, v122
	v_cvt_f32_i32_e32 v124, v124
	v_cvt_f32_i32_e32 v125, v125
	v_cmp_ge_i32_e64 s[0:1], v130, v123
	v_mul_f32_e32 v124, v146, v124
	v_mul_f32_e32 v125, v146, v125
	v_exp_f32_e32 v124, v124
	v_exp_f32_e32 v125, v125
	s_nop 0
	v_pk_mul_f32 v[118:119], v[124:125], v[118:119]
	v_or_b32_e32 v124, 35, v149
	v_or_b32_e32 v125, 34, v149
	v_sub_u32_e32 v152, v130, v125
	v_sub_u32_e32 v153, v130, v124
	v_cvt_f32_i32_e32 v152, v152
	v_cvt_f32_i32_e32 v153, v153
	v_cvt_pk_bf16_f32 v118, v118, v119
	v_cndmask_b32_e64 v119, 0, v118, s[0:1]
	v_mul_f32_e32 v152, v146, v152
	v_mul_f32_e32 v153, v146, v153
	v_exp_f32_e32 v152, v152
	v_exp_f32_e32 v153, v153
	v_lshrrev_b32_e32 v118, 16, v118
	v_cmp_ge_i32_e64 s[0:1], v130, v122
	v_pk_mul_f32 v[120:121], v[152:153], v[120:121]
	s_nop 0
	v_cndmask_b32_e64 v118, 0, v118, s[0:1]
	v_cvt_pk_bf16_f32 v120, v120, v121
	v_cmp_ge_i32_e64 s[0:1], v130, v125
	v_perm_b32 v152, v118, v119, s7
	v_or_b32_e32 v118, 49, v149
	v_cndmask_b32_e64 v121, 0, v120, s[0:1]
	v_lshrrev_b32_e32 v120, 16, v120
	v_cmp_ge_i32_e64 s[0:1], v130, v124
; DEV uint2 pack4(f32x4 v) { uint2 r; r.x = pack2(v[0], v[1]); r.y = pack2(v[2], v[3]); return r; }
; DEV float ex2(float x) { return __builtin_amdgcn_exp2f(x); }
; DEV void ret_item(const Params& p, int h, int c, bf16_t* lds) {
;     ...
; #pragma unroll
;   for (int i = 0; i < 2; i++) {
;     const int q = wm * 32 + i * 16 + lr;
; #pragma unroll
;     for (int j = 0; j < 4; j++) {
;       f32x4 v;
; #pragma unroll
;       for (int r = 0; r < 4; r++) {
;         const int key = wn * 64 + j * 16 + lg * 4 + r;
;         v[r] = (key <= q) ? s[i][j][r] * ex2(l2g * (float)(q - key)) : 0.f;
;       }
;       *(uint2*)(Ks + q * PS + wn * 64 + j * 16 + lg * 4) = pack4(v);
;     }
;   }
; #pragma unroll
;   for (int i = 0; i < 8; i++) *(u32x4*)(Big + (lrow + i * 32) * PS + lc8) = vpre[i];
;   __syncthreads();
	v_or_b32_e32 v119, 48, v149
	s_nop 0
	v_cndmask_b32_e64 v120, 0, v120, s[0:1]
	v_perm_b32 v153, v120, v121, s7
	v_sub_u32_e32 v120, v130, v119
	v_sub_u32_e32 v121, v130, v118
	v_cvt_f32_i32_e32 v120, v120
	v_cvt_f32_i32_e32 v121, v121
	v_cmp_ge_i32_e64 s[0:1], v130, v119
	v_mul_f32_e32 v120, v146, v120
	v_mul_f32_e32 v121, v146, v121
	v_exp_f32_e32 v120, v120
	v_exp_f32_e32 v121, v121
	s_nop 0
	v_pk_mul_f32 v[154:155], v[120:121], v[114:115]
	v_or_b32_e32 v120, 50, v149
	v_sub_u32_e32 v114, v130, v120
	v_cvt_f32_i32_e32 v114, v114
	v_or_b32_e32 v115, 51, v149
	v_mul_f32_e32 v114, v146, v114
	v_exp_f32_e32 v156, v114
	v_sub_u32_e32 v114, v130, v115
	v_cvt_f32_i32_e32 v114, v114
	v_mul_f32_e32 v114, v146, v114
	v_exp_f32_e32 v157, v114
	v_cvt_pk_bf16_f32 v114, v154, v155
	v_cndmask_b32_e64 v121, 0, v114, s[0:1]
	v_lshrrev_b32_e32 v114, 16, v114
	v_pk_mul_f32 v[116:117], v[156:157], v[116:117]
	v_cmp_ge_i32_e64 s[0:1], v130, v118
	v_cvt_pk_bf16_f32 v116, v116, v117
	s_nop 0
	v_cndmask_b32_e64 v114, 0, v114, s[0:1]
	v_cmp_ge_i32_e64 s[0:1], v130, v120
	s_nop 1
	v_cndmask_b32_e64 v117, 0, v116, s[0:1]
	v_lshrrev_b32_e32 v116, 16, v116
	v_cmp_ge_i32_e64 s[0:1], v130, v115
	s_nop 1
	v_cndmask_b32_e64 v116, 0, v116, s[0:1]
	v_perm_b32 v117, v116, v117, s7
	v_perm_b32 v116, v114, v121, s7
	v_or_b32_e32 v114, 16, v130
	ds_write2_b64 v151, v[152:153], v[116:117] offset0:8 offset1:12
	v_mad_u64_u32 v[116:117], s[0:1], v114, s10, v[0:1]
	v_sub_u32_e32 v0, v114, v149
	v_cvt_f32_i32_e32 v0, v0
	v_cmp_ge_i32_e64 s[0:1], v114, v149
	v_mul_f32_e32 v0, v146, v0
	v_exp_f32_e32 v0, v0
	s_nop 0
	v_mul_f32_e32 v0, v0, v110
	v_sub_u32_e32 v110, v114, v150
	v_cvt_f32_i32_e32 v110, v110
	v_cndmask_b32_e64 v0, 0, v0, s[0:1]
	v_cmp_gt_i32_e64 s[0:1], v114, v149
	v_mul_f32_e32 v110, v146, v110
	v_exp_f32_e32 v110, v110
	s_nop 0
	v_mul_f32_e32 v110, v110, v111
	v_cndmask_b32_e64 v117, 0, v110, s[0:1]
	v_sub_u32_e32 v110, v114, v127
	v_sub_u32_e32 v111, v114, v126
	v_cvt_f32_i32_e32 v110, v110
	v_cvt_f32_i32_e32 v111, v111
	v_cmp_ge_i32_e64 s[0:1], v114, v127
	v_mul_f32_e32 v110, v146, v110
	v_mul_f32_e32 v111, v146, v111
	v_exp_f32_e32 v110, v110
	v_exp_f32_e32 v111, v111
	s_nop 0
	v_pk_mul_f32 v[110:111], v[110:111], v[112:113]
	v_cvt_pk_bf16_f32 v112, v0, v117
	v_cvt_pk_bf16_f32 v0, v110, v111
	v_cndmask_b32_e64 v110, 0, v0, s[0:1]
	v_lshrrev_b32_e32 v0, 16, v0
	v_cmp_ge_i32_e64 s[0:1], v114, v126
	s_nop 1
	v_cndmask_b32_e64 v0, 0, v0, s[0:1]
	v_perm_b32 v113, v0, v110, s7
	v_mul_f32_e32 v0, v147, v106
	v_sub_u32_e32 v106, v114, v148
	v_cvt_f32_i32_e32 v106, v106
	v_cndmask_b32_e64 v0, v0, 0, vcc
	v_cmp_ge_i32_e32 vcc, v114, v148
	v_mul_f32_e32 v106, v146, v106
	v_exp_f32_e32 v106, v106
	s_nop 0
	v_mul_f32_e32 v106, v106, v107
	v_cndmask_b32_e32 v110, 0, v106, vcc
	v_sub_u32_e32 v106, v114, v129
	v_sub_u32_e32 v107, v114, v128
	v_cvt_f32_i32_e32 v106, v106
	v_cvt_f32_i32_e32 v107, v107
	v_cmp_ge_i32_e32 vcc, v114, v129
	v_mul_f32_e32 v106, v146, v106
	v_mul_f32_e32 v107, v146, v107
	v_exp_f32_e32 v106, v106
	v_exp_f32_e32 v107, v107
	s_nop 0
	v_pk_mul_f32 v[106:107], v[106:107], v[108:109]
	v_cvt_pk_bf16_f32 v108, v0, v110
	v_cvt_pk_bf16_f32 v0, v106, v107
	v_cndmask_b32_e32 v106, 0, v0, vcc
	v_lshrrev_b32_e32 v0, 16, v0
	v_cmp_ge_i32_e32 vcc, v114, v128
	v_sub_u32_e32 v107, v114, v122
	v_cvt_f32_i32_e32 v107, v107
	v_cndmask_b32_e32 v0, 0, v0, vcc
	v_perm_b32 v109, v0, v106, s7
	v_sub_u32_e32 v106, v114, v123
	v_cvt_f32_i32_e32 v106, v106
	v_mul_f32_e32 v107, v146, v107
	v_exp_f32_e32 v107, v107
	v_cmp_ge_i32_e32 vcc, v114, v123
	v_mul_f32_e32 v106, v146, v106
	v_exp_f32_e32 v106, v106
	v_add_u32_e32 v0, 0x8800, v116
	ds_write2_b64 v0, v[112:113], v[108:109] offset1:4
	v_pk_mul_f32 v[102:103], v[106:107], v[102:103]
	v_sub_u32_e32 v106, v114, v125
	v_sub_u32_e32 v107, v114, v124
	v_cvt_f32_i32_e32 v106, v106
	v_cvt_f32_i32_e32 v107, v107
	v_cvt_pk_bf16_f32 v102, v102, v103
	v_mul_f32_e32 v106, v146, v106
	v_mul_f32_e32 v107, v146, v107
	v_exp_f32_e32 v106, v106
	v_exp_f32_e32 v107, v107
	s_nop 0
	v_pk_mul_f32 v[104:105], v[106:107], v[104:105]
	v_cndmask_b32_e32 v106, 0, v102, vcc
	v_lshrrev_b32_e32 v102, 16, v102
	v_cmp_ge_i32_e32 vcc, v114, v122
	v_cvt_pk_bf16_f32 v103, v104, v105
	v_sub_u32_e32 v105, v114, v118
	v_cndmask_b32_e32 v102, 0, v102, vcc
	v_cmp_ge_i32_e32 vcc, v114, v125
	v_cvt_f32_i32_e32 v105, v105
	v_perm_b32 v102, v102, v106, s7
	v_cndmask_b32_e32 v104, 0, v103, vcc
	v_lshrrev_b32_e32 v103, 16, v103
	v_cmp_ge_i32_e32 vcc, v114, v124
	v_mul_f32_e32 v105, v146, v105
	v_exp_f32_e32 v105, v105
	v_cndmask_b32_e32 v103, 0, v103, vcc
	v_perm_b32 v103, v103, v104, s7
	v_sub_u32_e32 v104, v114, v119
	v_cvt_f32_i32_e32 v104, v104
	v_cmp_ge_i32_e32 vcc, v114, v119
	v_mul_f32_e32 v104, v146, v104
	v_exp_f32_e32 v104, v104
	s_nop 0
	v_pk_mul_f32 v[74:75], v[104:105], v[74:75]
	v_sub_u32_e32 v104, v114, v120
	v_sub_u32_e32 v105, v114, v115
	v_cvt_f32_i32_e32 v104, v104
	v_cvt_f32_i32_e32 v105, v105
	v_cvt_pk_bf16_f32 v74, v74, v75
	v_mul_f32_e32 v104, v146, v104
	v_mul_f32_e32 v105, v146, v105
	v_exp_f32_e32 v104, v104
	v_exp_f32_e32 v105, v105
	s_nop 0
	v_pk_mul_f32 v[76:77], v[104:105], v[76:77]
	v_cndmask_b32_e32 v104, 0, v74, vcc
	v_lshrrev_b32_e32 v74, 16, v74
	v_cmp_ge_i32_e32 vcc, v114, v118
	v_cvt_pk_bf16_f32 v75, v76, v77
	s_nop 0
	v_cndmask_b32_e32 v74, 0, v74, vcc
	v_cmp_ge_i32_e32 vcc, v114, v120
	v_perm_b32 v74, v74, v104, s7
	s_nop 0
	v_cndmask_b32_e32 v76, 0, v75, vcc
	v_lshrrev_b32_e32 v75, 16, v75
	v_cmp_ge_i32_e32 vcc, v114, v115
	s_nop 1
	v_cndmask_b32_e32 v75, 0, v75, vcc
	v_perm_b32 v75, v75, v76, s7
	ds_write2_b64 v0, v[102:103], v[74:75] offset0:8 offset1:12
	s_waitcnt vmcnt(7)
	ds_write_b128 v143, v[2:5]
	s_waitcnt vmcnt(6)
	ds_write_b128 v143, v[6:9] offset:8704
	s_waitcnt vmcnt(5)
	ds_write_b128 v143, v[10:13] offset:17408
	s_waitcnt vmcnt(4)
	ds_write_b128 v143, v[14:17] offset:26112
	s_waitcnt vmcnt(3)
	ds_write_b128 v143, v[18:21] offset:34816
	s_waitcnt vmcnt(2)
	ds_write_b128 v143, v[22:25] offset:43520
	s_waitcnt vmcnt(1)
	ds_write_b128 v143, v[26:29] offset:52224
	s_waitcnt vmcnt(0)
	ds_write_b128 v143, v[30:33] offset:60928
	s_waitcnt lgkmcnt(0)
	s_barrier
; #define MFMA(a, b, c) __builtin_amdgcn_mfma_f32_16x16x32_bf16(a, b, c, 0, 0, 0)
; DEV void ret_item(const Params& p, int h, int c, bf16_t* lds) {
;     ...
; #pragma unroll
;   for (int ks = 0; ks < 4; ks++) {
;     bf16x8 a0 = ldfrag(Ks, PS, wm * 32 + lr, ks * 32 + lg * 8);
;     bf16x8 a1 = ldfrag(Ks, PS, wm * 32 + 16 + lr, ks * 32 + lg * 8);
; #pragma unroll
;     for (int j = 0; j < 8; j++) {
;       bf16x8 bb = ldfrag(Big, PS, wn * 128 + j * 16 + lr, ks * 32 + lg * 8);
;       o[0][j] = MFMA(bb, a0, o[0][j]);
;       o[1][j] = MFMA(bb, a1, o[1][j]);
;     }
;     __builtin_amdgcn_sched_barrier(0);
;   }
	ds_read_b128 v[14:17], v136 offset:34816
	ds_read_b128 v[10:13], v136 offset:39168
	ds_read_b128 v[6:9], v137
	ds_read_b128 v[74:77], v137 offset:13056
	s_waitcnt lgkmcnt(0)
	v_mfma_f32_16x16x32_bf16 v[62:65], v[74:77], v[14:17], v[62:65]
	ds_read_b128 v[18:21], v137 offset:4352
	ds_read_b128 v[26:29], v137 offset:8704
	v_mfma_f32_16x16x32_bf16 v[70:73], v[74:77], v[10:13], v[70:73]
	ds_read_b128 v[224:227], v137 offset:17408
	ds_read_b128 v[220:223], v137 offset:21760
	s_waitcnt lgkmcnt(1)
	v_mfma_f32_16x16x32_bf16 v[58:61], v[224:227], v[14:17], v[58:61]
	v_mfma_f32_16x16x32_bf16 v[66:69], v[224:227], v[10:13], v[66:69]
	ds_read_b128 v[74:77], v137 offset:26112
	s_waitcnt lgkmcnt(1)
	v_mfma_f32_16x16x32_bf16 v[46:49], v[220:223], v[14:17], v[46:49]
	v_mfma_f32_16x16x32_bf16 v[54:57], v[220:223], v[10:13], v[54:57]
	s_waitcnt lgkmcnt(0)
	v_mfma_f32_16x16x32_bf16 v[42:45], v[74:77], v[14:17], v[42:45]
	v_mfma_f32_16x16x32_bf16 v[50:53], v[74:77], v[10:13], v[50:53]
	ds_read_b128 v[74:77], v137 offset:30464
	v_mfma_f32_16x16x32_bf16 v[2:5], v[6:9], v[14:17], v[94:97]
	v_mfma_f32_16x16x32_bf16 v[6:9], v[6:9], v[10:13], v[98:101]
	v_mfma_f32_16x16x32_bf16 v[22:25], v[18:21], v[14:17], v[82:85]
	v_mfma_f32_16x16x32_bf16 v[18:21], v[18:21], v[10:13], v[90:93]
	v_mfma_f32_16x16x32_bf16 v[30:33], v[26:29], v[14:17], v[78:81]
	v_mfma_f32_16x16x32_bf16 v[26:29], v[26:29], v[10:13], v[86:89]
	s_waitcnt lgkmcnt(0)
	v_mfma_f32_16x16x32_bf16 v[14:17], v[74:77], v[14:17], v[34:37]
	v_mfma_f32_16x16x32_bf16 v[10:13], v[74:77], v[10:13], v[38:41]
	s_nop 1
	ds_read_b128 v[34:37], v136 offset:34880
	ds_read_b128 v[38:41], v136 offset:39232
	ds_read_b128 v[224:227], v140
	ds_read_b128 v[220:223], v138 offset:4352
	s_waitcnt lgkmcnt(1)
	v_mfma_f32_16x16x32_bf16 v[2:5], v[224:227], v[34:37], v[2:5]
	v_mfma_f32_16x16x32_bf16 v[6:9], v[224:227], v[38:41], v[6:9]
	ds_read_b128 v[224:227], v138 offset:8704
	s_waitcnt lgkmcnt(1)
	v_mfma_f32_16x16x32_bf16 v[22:25], v[220:223], v[34:37], v[22:25]
	v_mfma_f32_16x16x32_bf16 v[18:21], v[220:223], v[38:41], v[18:21]
	ds_read_b128 v[220:223], v138 offset:13056
	s_waitcnt lgkmcnt(1)
	v_mfma_f32_16x16x32_bf16 v[30:33], v[224:227], v[34:37], v[30:33]
	v_mfma_f32_16x16x32_bf16 v[26:29], v[224:227], v[38:41], v[26:29]
	ds_read_b128 v[224:227], v138 offset:17408
	s_waitcnt lgkmcnt(1)
	v_mfma_f32_16x16x32_bf16 v[62:65], v[220:223], v[34:37], v[62:65]
	v_mfma_f32_16x16x32_bf16 v[70:73], v[220:223], v[38:41], v[70:73]
	ds_read_b128 v[220:223], v138 offset:21760
	s_waitcnt lgkmcnt(1)
	v_mfma_f32_16x16x32_bf16 v[58:61], v[224:227], v[34:37], v[58:61]
	v_mfma_f32_16x16x32_bf16 v[66:69], v[224:227], v[38:41], v[66:69]
	ds_read_b128 v[224:227], v138 offset:26112
	s_waitcnt lgkmcnt(1)
	v_mfma_f32_16x16x32_bf16 v[46:49], v[220:223], v[34:37], v[46:49]
	v_mfma_f32_16x16x32_bf16 v[54:57], v[220:223], v[38:41], v[54:57]
	ds_read_b128 v[74:77], v138 offset:30464
	s_waitcnt lgkmcnt(1)
	v_mfma_f32_16x16x32_bf16 v[42:45], v[224:227], v[34:37], v[42:45]
	v_mfma_f32_16x16x32_bf16 v[50:53], v[224:227], v[38:41], v[50:53]
	s_waitcnt lgkmcnt(0)
	v_mfma_f32_16x16x32_bf16 v[14:17], v[74:77], v[34:37], v[14:17]
	v_mfma_f32_16x16x32_bf16 v[10:13], v[74:77], v[38:41], v[10:13]
	ds_read_b128 v[34:37], v136 offset:34944
	ds_read_b128 v[38:41], v136 offset:39296
	ds_read_b128 v[224:227], v142
	ds_read_b128 v[220:223], v139 offset:4352
	s_waitcnt lgkmcnt(1)
	v_mfma_f32_16x16x32_bf16 v[2:5], v[224:227], v[34:37], v[2:5]
	v_mfma_f32_16x16x32_bf16 v[6:9], v[224:227], v[38:41], v[6:9]
	ds_read_b128 v[224:227], v139 offset:8704
	s_waitcnt lgkmcnt(1)
	v_mfma_f32_16x16x32_bf16 v[22:25], v[220:223], v[34:37], v[22:25]
	v_mfma_f32_16x16x32_bf16 v[18:21], v[220:223], v[38:41], v[18:21]
	ds_read_b128 v[220:223], v139 offset:13056
	s_waitcnt lgkmcnt(1)
	v_mfma_f32_16x16x32_bf16 v[30:33], v[224:227], v[34:37], v[30:33]
	v_mfma_f32_16x16x32_bf16 v[26:29], v[224:227], v[38:41], v[26:29]
	ds_read_b128 v[74:77], v139 offset:17408
	s_waitcnt lgkmcnt(1)
; #define MFMA(a, b, c) __builtin_amdgcn_mfma_f32_16x16x32_bf16(a, b, c, 0, 0, 0)
; DEV float shfl_xor_l(float v, int m, int lane) { return __int_as_float(__builtin_amdgcn_ds_bpermute((lane ^ m) << 2, __float_as_int(v))); }
; DEV void ret_item(const Params& p, int h, int c, bf16_t* lds) {
;     ...
; #pragma unroll
;   for (int ks = 0; ks < 4; ks++) {
;     bf16x8 a0 = ldfrag(Ks, PS, wm * 32 + lr, ks * 32 + lg * 8);
;     bf16x8 a1 = ldfrag(Ks, PS, wm * 32 + 16 + lr, ks * 32 + lg * 8);
; #pragma unroll
;     for (int j = 0; j < 8; j++) {
;       bf16x8 bb = ldfrag(Big, PS, wn * 128 + j * 16 + lr, ks * 32 + lg * 8);
;       o[0][j] = MFMA(bb, a0, o[0][j]);
;       o[1][j] = MFMA(bb, a1, o[1][j]);
;     }
;     __builtin_amdgcn_sched_barrier(0);
;   }
; #pragma unroll
;   for (int i = 0; i < 2; i++) {
;     float ss = 0.f;
; #pragma unroll
;     for (int j = 0; j < 8; j++)
; #pragma unroll
;       for (int r = 0; r < 4; r++) ss += o[i][j][r] * o[i][j][r];
;     ss += shfl_xor_l(ss, 16, lane);
;     ss += shfl_xor_l(ss, 32, lane);
;     if (lg == 0) RED[(wm * 32 + i * 16 + lr) * 2 + wn] = ss;
	v_mfma_f32_16x16x32_bf16 v[62:65], v[220:223], v[34:37], v[62:65]
	v_mfma_f32_16x16x32_bf16 v[70:73], v[220:223], v[38:41], v[70:73]
	s_waitcnt lgkmcnt(0)
	v_mfma_f32_16x16x32_bf16 v[58:61], v[74:77], v[34:37], v[58:61]
	v_mfma_f32_16x16x32_bf16 v[66:69], v[74:77], v[38:41], v[66:69]
	ds_read_b128 v[74:77], v139 offset:21760
	s_waitcnt lgkmcnt(0)
	v_mfma_f32_16x16x32_bf16 v[78:81], v[74:77], v[34:37], v[46:49]
	s_nop 2
	ds_read_b128 v[46:49], v139 offset:26112
	v_mfma_f32_16x16x32_bf16 v[54:57], v[74:77], v[38:41], v[54:57]
	s_waitcnt lgkmcnt(0)
	v_mfma_f32_16x16x32_bf16 v[74:77], v[46:49], v[34:37], v[42:45]
	s_nop 2
	ds_read_b128 v[42:45], v139 offset:30464
	v_mfma_f32_16x16x32_bf16 v[82:85], v[46:49], v[38:41], v[50:53]
	s_waitcnt lgkmcnt(0)
	v_mfma_f32_16x16x32_bf16 v[86:89], v[42:45], v[34:37], v[14:17]
	v_mfma_f32_16x16x32_bf16 v[90:93], v[42:45], v[38:41], v[10:13]
	ds_read_b128 v[94:97], v136 offset:35008
	ds_read_b128 v[98:101], v136 offset:39360
	s_nop 0
	ds_read_b128 v[10:13], v144
	ds_read_b128 v[14:17], v141 offset:21760
	s_waitcnt lgkmcnt(1)
	v_mfma_f32_16x16x32_bf16 v[34:37], v[10:13], v[94:97], v[2:5]
	v_mfma_f32_16x16x32_bf16 v[2:5], v[10:13], v[98:101], v[6:9]
	ds_read_b128 v[10:13], v141 offset:13056
	s_nop 1
	ds_read_b128 v[6:9], v141 offset:4352
	s_waitcnt lgkmcnt(0)
	v_mfma_f32_16x16x32_bf16 v[42:45], v[6:9], v[94:97], v[22:25]
	v_mfma_f32_16x16x32_bf16 v[18:21], v[6:9], v[98:101], v[18:21]
	ds_read_b128 v[6:9], v141 offset:8704
	v_mfma_f32_16x16x32_bf16 v[50:53], v[10:13], v[94:97], v[62:65]
	v_mfma_f32_16x16x32_bf16 v[22:25], v[10:13], v[98:101], v[70:73]
	ds_read_b128 v[10:13], v141 offset:17408
	s_waitcnt lgkmcnt(1)
	v_mfma_f32_16x16x32_bf16 v[38:41], v[6:9], v[94:97], v[30:33]
	v_mfma_f32_16x16x32_bf16 v[6:9], v[6:9], v[98:101], v[26:29]
	s_nop 1
	ds_read_b128 v[30:33], v141 offset:30464
	s_waitcnt lgkmcnt(1)
	v_mfma_f32_16x16x32_bf16 v[46:49], v[10:13], v[94:97], v[58:61]
	v_mfma_f32_16x16x32_bf16 v[58:61], v[14:17], v[94:97], v[78:81]
	v_mfma_f32_16x16x32_bf16 v[26:29], v[14:17], v[98:101], v[54:57]
	ds_read_b128 v[14:17], v141 offset:26112
	v_mfma_f32_16x16x32_bf16 v[10:13], v[10:13], v[98:101], v[66:69]
	s_waitcnt lgkmcnt(0)
	v_mfma_f32_16x16x32_bf16 v[54:57], v[14:17], v[94:97], v[74:77]
	v_mfma_f32_16x16x32_bf16 v[14:17], v[14:17], v[98:101], v[82:85]
	v_mfma_f32_16x16x32_bf16 v[62:65], v[30:33], v[94:97], v[86:89]
	v_mfma_f32_16x16x32_bf16 v[30:33], v[30:33], v[98:101], v[90:93]
	v_mul_f32_e32 v68, v35, v35
	v_fmac_f32_e32 v68, v34, v34
	v_fmac_f32_e32 v68, v36, v36
	v_fmac_f32_e32 v68, v37, v37
	v_fmac_f32_e32 v68, v42, v42
	v_fmac_f32_e32 v68, v43, v43
	v_fmac_f32_e32 v68, v44, v44
	v_fmac_f32_e32 v68, v45, v45
	v_fmac_f32_e32 v68, v38, v38
	v_fmac_f32_e32 v68, v39, v39
	v_fmac_f32_e32 v68, v40, v40
	v_fmac_f32_e32 v68, v41, v41
	v_fmac_f32_e32 v68, v50, v50
	v_fmac_f32_e32 v68, v51, v51
	v_fmac_f32_e32 v68, v52, v52
	v_fmac_f32_e32 v68, v53, v53
	v_fmac_f32_e32 v68, v46, v46
	v_fmac_f32_e32 v68, v47, v47
	v_fmac_f32_e32 v68, v48, v48
	v_fmac_f32_e32 v68, v49, v49
	v_fmac_f32_e32 v68, v58, v58
	v_fmac_f32_e32 v68, v59, v59
	v_fmac_f32_e32 v68, v60, v60
	v_fmac_f32_e32 v68, v61, v61
	v_fmac_f32_e32 v68, v54, v54
	v_fmac_f32_e32 v68, v55, v55
	v_fmac_f32_e32 v68, v56, v56
	v_fmac_f32_e32 v68, v57, v57
	v_fmac_f32_e32 v68, v62, v62
	v_fmac_f32_e32 v68, v63, v63
	v_lshlrev_b32_e32 v0, 2, v135
	v_fmac_f32_e32 v68, v64, v64
	v_xor_b32_e32 v66, 64, v0
	v_fmac_f32_e32 v68, v65, v65
	ds_bpermute_b32 v69, v66, v68
	v_xor_b32_e32 v0, 0x80, v0
	v_readlane_b32 s0, v255, 9
	v_lshlrev_b32_e32 v70, 8, v131
	v_lshlrev_b32_e32 v71, 3, v132
	s_waitcnt lgkmcnt(0)
	v_add_f32_e32 v68, v68, v69
	ds_bpermute_b32 v69, v0, v68
	v_lshl_add_u32 v67, v134, 2, s0
	v_cmp_gt_u32_e32 vcc, 16, v135
	v_add3_u32 v67, v67, v70, v71
	s_and_saveexec_b64 s[0:1], vcc
	s_cbranch_execz .LBB0_702
	s_waitcnt lgkmcnt(0)
	v_add_f32_e32 v68, v68, v69
	ds_write_b32 v67, v68

; DEV float shfl_xor_l(float v, int m, int lane) { return __int_as_float(__builtin_amdgcn_ds_bpermute((lane ^ m) << 2, __float_as_int(v))); }
; DEV float ex2(float x) { return __builtin_amdgcn_exp2f(x); }
; DEV void attn_item(const Params& p, int layer, int h, int qb, float lam, bf16_t* lds) {
;     ...
;     float al[2];
; #pragma unroll
;     for (int i = 0; i < 2; i++) {
;       float mx = -1e30f;
; #pragma unroll
;       for (int j = 0; j < 8; j++)
; #pragma unroll
;         for (int r = 0; r < 4; r++) mx = fmaxf(mx, s[i][j][r]);
;       mx = fmaxf(mx, shfl_xor_l(mx, 16, lane));
;       mx = fmaxf(mx, shfl_xor_l(mx, 32, lane));
;       const float mold = i == 0 ? mrun0 : mrun1;
;       const float mnew = (mx > mold + 8.f) ? mx : mold;
;       al[i] = ex2(mold - mnew);
.LBB0_710:
	v_max3_f32 v0, v176, s68, v177
	v_max3_f32 v0, v0, v178, v179
	v_max3_f32 v2, v168, s68, v169
	v_max3_f32 v0, v0, v172, v173
	v_max3_f32 v2, v2, v170, v171
	v_max3_f32 v0, v0, v174, v175
	v_max3_f32 v2, v2, v164, v165
	v_max3_f32 v0, v0, v160, v161
	v_max3_f32 v2, v2, v166, v167
	v_max3_f32 v0, v0, v162, v163
	v_max3_f32 v2, v2, v152, v153
	v_max3_f32 v0, v0, v156, v157
	v_max3_f32 v2, v2, v154, v155
	v_max3_f32 v0, v0, v158, v159
	v_max3_f32 v2, v2, v148, v149
	v_max3_f32 v0, v0, v144, v145
	v_max3_f32 v2, v2, v150, v151
	v_max3_f32 v0, v0, v146, v147
	v_max3_f32 v2, v2, v136, v137
	v_max3_f32 v0, v0, v140, v141
	v_max3_f32 v2, v2, v138, v139
	v_max3_f32 v0, v0, v142, v143
	v_max3_f32 v2, v2, v132, v133
	v_max3_f32 v0, v0, v128, v129
	v_max3_f32 v2, v2, v134, v135
	v_max3_f32 v0, v0, v130, v131
	v_max3_f32 v2, v2, v120, v121
	v_max3_f32 v0, v0, v124, v125
	v_max3_f32 v2, v2, v122, v123
	v_max3_f32 v0, v0, v126, v127
	v_mov_b32_e32 v3, v0
	v_mov_b32_e32 v195, v0
	v_max3_f32 v2, v2, v116, v117
	v_max3_f32 v194, v2, v118, v119
	v_permlane16_swap_b32_e32 v3, v195
	v_mov_b32_e32 v196, v194
	v_mov_b32_e32 v197, v194
	v_max_f32_e32 v0, v3, v195
	v_mov_b32_e32 v3, v0
	v_permlane16_swap_b32_e32 v196, v197
	v_mov_b32_e32 v195, v0
	v_max_f32_e32 v194, v196, v197
	v_mov_b32_e32 v196, v194
	v_permlane32_swap_b32_e32 v3, v195
	v_mov_b32_e32 v197, v194
	v_max_f32_e32 v0, v3, v195
	v_sub_f32_e32 v3, v193, v206
	v_permlane32_swap_b32_e32 v196, v197
	v_sub_f32_e32 v2, v192, v212
	v_max_f32_e32 v196, v196, v197
	s_mov_b32 s0, 0x41000000
	v_pk_add_f32 v[194:195], v[2:3], s[0:1] op_sel_hi:[1,0]
	v_cmp_gt_f32_e32 vcc, v0, v195
	s_nop 1
	v_cndmask_b32_e32 v249, v3, v0, vcc
	v_cmp_gt_f32_e32 vcc, v196, v194
	s_nop 1
	v_cndmask_b32_e32 v248, v2, v196, vcc
	v_or3_b32 v194, v2, v3, v249
	v_or_b32_e32 v194, v194, v248
	v_cmp_ne_u32_e32 vcc, 0, v194
	s_cbranch_vccnz .Lattc_slow
	v_mov_b32_e32 v2, 1.0
	v_mov_b32_e32 v3, 1.0
	s_branch .LBB0_707
